# residual epilogue: x_old loads prefetched one 16-row block ahead (two register sets)
# baseline (speedup 1.0000x reference)
; DI int TIDX() { int t = (int)threadIdx.x; asm volatile("" : "+v"(t)); return t; }
; DI unsigned pk2(float lo, float hi) { f32x2 v = {lo, hi}; return __builtin_bit_cast(unsigned, __builtin_convertvector(v, bfx2)); }
; DI void resid_tile(const Params& p, const bf16_t* A, int K, const bf16_t* W, const float* xold, const float* gnext, int tm, int tn, bf16_t* smem) {
;     ...
;   const int lane = TIDX() & 63, wid = TIDX() >> 6, wm = wid >> 2, wn = wid & 3, l15 = lane & 15, quad = lane >> 4;
;   bf16_t* stg = smem + wid * STG_WAVE;
; #pragma unroll
;   for (int i = 0; i < 8; ++i) {
;     const int t = tm * 256 + wm * 128 + i * 16 + l15, c0 = tn * 256 + wn * 64 + quad * 4; float s = 0.f;
; #pragma unroll
;     for (int j = 0; j < 4; ++j) {
;       const size_t off = (size_t)t * D_ + c0 + j * 16;
;       const f32x4 xn = *(const f32x4*)(xold + off) + acc[i][j];
;       *(f32x4*)(p.out + off) = xn;
;       s += xn[0] * xn[0] + xn[1] * xn[1] + xn[2] * xn[2] + xn[3] * xn[3];
;       if (gnext) { const f32x4 gv = *(const f32x4*)(gnext + c0 + j * 16); *(u32x2*)(stg + (i * 16 + l15) * STG_LD + j * 16 + quad * 4) = (u32x2){pk2(xn[0] * gv[0], xn[1] * gv[1]), pk2(xn[2] * gv[2], xn[3] * gv[3])}; }
;     }
.Lgm5_exit:
	v_mfma_f32_16x16x32_bf16 v[28:31], v[178:181], v[242:245], v[28:31]
	v_mfma_f32_16x16x32_bf16 v[8:11], v[178:181], v[246:249], v[8:11]
	v_mfma_f32_16x16x32_bf16 v[24:27], v[182:185], v[242:245], v[24:27]
	v_mfma_f32_16x16x32_bf16 v[4:7], v[182:185], v[246:249], v[4:7]
	v_mfma_f32_16x16x32_bf16 v[20:23], v[186:189], v[242:245], v[20:23]
	v_mfma_f32_16x16x32_bf16 v[0:3], v[186:189], v[246:249], v[0:3]
	v_mfma_f32_16x16x32_bf16 v[16:19], v[190:193], v[242:245], v[16:19]
	v_mfma_f32_16x16x32_bf16 v[12:15], v[190:193], v[246:249], v[12:15]
	s_nop 7
	s_waitcnt vmcnt(0)
	v_mov_b32_e32 v145, v220
	v_mov_b32_e32 v112, v220
	s_lshl_b32 s12, s14, 8
	v_ashrrev_i32_e32 v118, 6, v112
	v_ashrrev_i32_e32 v112, 1, v112
	v_and_b32_e32 v112, 0xffffff80, v112
	v_and_b32_e32 v144, 3, v118
	v_and_b32_e32 v119, 15, v145
	v_lshl_add_u32 v132, s0, 8, v112
	v_lshrrev_b32_e32 v112, 2, v145
	v_or_b32_e32 v138, v132, v119
	v_lshlrev_b32_e32 v142, 6, v144
	v_and_b32_e32 v120, 12, v112
	v_or3_b32 v136, v120, s12, v142
	v_ashrrev_i32_e32 v139, 31, v138
	v_ashrrev_i32_e32 v137, 31, v136
	v_lshlrev_b64 v[112:113], 10, v[138:139]
	v_lshl_add_u64 v[112:113], v[112:113], 0, v[136:137]
	v_readlane_b32 s40, v241, 8
	v_lshlrev_b64 v[116:117], 2, v[112:113]
	v_readlane_b32 s41, v241, 9
	v_readlane_b32 s42, v241, 10
	v_readlane_b32 s43, v241, 11
	v_lshl_add_u64 v[124:125], s[40:41], 0, v[116:117]
	global_load_dwordx4 v[164:167], v[124:125], off
	global_load_dwordx4 v[168:171], v[124:125], off offset:64
	global_load_dwordx4 v[172:175], v[124:125], off offset:128
	global_load_dwordx4 v[192:195], v[124:125], off offset:192
	s_mov_b32 s98, 0x10000
	s_mov_b32 s99, 0
	v_lshl_add_u64 v[212:213], v[124:125], 0, s[98:99]
	global_load_dwordx4 v[196:199], v[212:213], off
	global_load_dwordx4 v[200:203], v[212:213], off offset:64
	global_load_dwordx4 v[204:207], v[212:213], off offset:128
	global_load_dwordx4 v[208:211], v[212:213], off offset:192
	v_readlane_b32 s44, v241, 12
	v_readlane_b32 s45, v241, 13
	v_readlane_b32 s46, v241, 14
	v_readlane_b32 s47, v241, 15
	v_readlane_b32 s48, v241, 16
	v_readlane_b32 s49, v241, 17
	v_readlane_b32 s50, v241, 18
	v_readlane_b32 s51, v241, 19
	v_readlane_b32 s52, v241, 20
	v_readlane_b32 s53, v241, 21
	v_readlane_b32 s54, v241, 22
	v_readlane_b32 s55, v241, 23
	v_mul_lo_u32 v143, v118, s25
	v_readlane_b32 s40, v241, 25
	v_readlane_b32 s28, v241, 2
	v_cndmask_b32_e64 v121, 0, 1, s[4:5]
	v_mul_u32_u24_e32 v118, 0x90, v119
	v_lshl_or_b32 v119, v120, 1, v143
	v_readlane_b32 s46, v241, 31
	v_readlane_b32 s47, v241, 32
	v_readlane_b32 s30, v241, 4
	v_readlane_b32 s31, v241, 5
	v_cmp_ne_u32_e64 s[0:1], 1, v121
	s_andn2_b64 vcc, exec, s[4:5]
	v_lshl_add_u64 v[134:135], v[136:137], 2, s[46:47]
	v_lshl_add_u64 v[140:141], s[30:31], 0, v[116:117]
	v_add_u32_e32 v133, v119, v118
	v_readlane_b32 s41, v241, 26
	v_readlane_b32 s42, v241, 27
	v_readlane_b32 s43, v241, 28
	v_readlane_b32 s44, v241, 29
	v_readlane_b32 s45, v241, 30
	v_readlane_b32 s48, v241, 33
	v_readlane_b32 s49, v241, 34
	v_readlane_b32 s50, v241, 35
	v_readlane_b32 s51, v241, 36
	v_readlane_b32 s52, v241, 37
	v_readlane_b32 s53, v241, 38
	v_readlane_b32 s54, v241, 39
	v_readlane_b32 s55, v241, 40
	v_readlane_b32 s29, v241, 3
	s_waitcnt vmcnt(4)
	v_pk_add_f32 v[114:115], v[158:159], v[166:167]
	v_pk_add_f32 v[112:113], v[156:157], v[164:165]
	global_store_dwordx4 v[140:141], v[112:115], off
	s_cbranch_vccnz .LBB0_913
	global_load_dwordx4 v[176:179], v[134:135], off
	global_load_dwordx4 v[180:183], v[134:135], off offset:64
	global_load_dwordx4 v[184:187], v[134:135], off offset:128
	global_load_dwordx4 v[188:191], v[134:135], off offset:192
	s_waitcnt vmcnt(3)
	v_pk_mul_f32 v[118:119], v[114:115], v[178:179]
	v_pk_mul_f32 v[116:117], v[112:113], v[176:177]
	s_nop 0
	v_cvt_pk_bf16_f32 v116, v116, v117
	v_cvt_pk_bf16_f32 v117, v118, v119
	ds_write_b64 v133, v[116:117]
.LBB0_913:
	s_and_b64 vcc, exec, s[0:1]
	v_pk_add_f32 v[118:119], v[154:155], v[170:171]
	v_pk_add_f32 v[116:117], v[152:153], v[168:169]
	global_store_dwordx4 v[140:141], v[116:119], off offset:64
	s_cbranch_vccnz .LBB0_915
	s_waitcnt vmcnt(3)
	v_pk_mul_f32 v[122:123], v[118:119], v[182:183]
	v_pk_mul_f32 v[120:121], v[116:117], v[180:181]
	s_nop 0
	v_cvt_pk_bf16_f32 v120, v120, v121
	v_cvt_pk_bf16_f32 v121, v122, v123
	ds_write_b64 v133, v[120:121] offset:32
.LBB0_915:
	s_and_b64 vcc, exec, s[0:1]
	v_pk_add_f32 v[122:123], v[150:151], v[174:175]
	v_pk_add_f32 v[120:121], v[148:149], v[172:173]
	global_store_dwordx4 v[140:141], v[120:123], off offset:128
	s_cbranch_vccnz .LBB0_917
	s_waitcnt vmcnt(3)
	v_pk_mul_f32 v[126:127], v[122:123], v[186:187]
	v_pk_mul_f32 v[146:147], v[120:121], v[184:185]
	s_nop 0
	v_cvt_pk_bf16_f32 v146, v146, v147
	v_cvt_pk_bf16_f32 v147, v126, v127
	ds_write_b64 v133, v[146:147] offset:64
.LBB0_917:
	s_and_b64 vcc, exec, s[0:1]
	v_pk_add_f32 v[126:127], v[130:131], v[194:195]
	v_pk_add_f32 v[124:125], v[128:129], v[192:193]
	global_store_dwordx4 v[140:141], v[124:127], off offset:192
	s_cbranch_vccnz .LBB0_919
	s_waitcnt vmcnt(3)
	v_pk_mul_f32 v[130:131], v[126:127], v[190:191]
	v_pk_mul_f32 v[128:129], v[124:125], v[188:189]
	s_nop 0
	v_cvt_pk_bf16_f32 v128, v128, v129
	v_cvt_pk_bf16_f32 v129, v130, v131
	ds_write_b64 v133, v[128:129] offset:96

; DI unsigned pk2(float lo, float hi) { f32x2 v = {lo, hi}; return __builtin_bit_cast(unsigned, __builtin_convertvector(v, bfx2)); }
; DI void resid_tile(const Params& p, const bf16_t* A, int K, const bf16_t* W, const float* xold, const float* gnext, int tm, int tn, bf16_t* smem) {
;     ...
; #pragma unroll
;   for (int i = 0; i < 8; ++i) {
;     const int t = tm * 256 + wm * 128 + i * 16 + l15, c0 = tn * 256 + wn * 64 + quad * 4; float s = 0.f;
; #pragma unroll
;     for (int j = 0; j < 4; ++j) {
;       const size_t off = (size_t)t * D_ + c0 + j * 16;
;       const f32x4 xn = *(const f32x4*)(xold + off) + acc[i][j];
;       *(f32x4*)(p.out + off) = xn;
;       s += xn[0] * xn[0] + xn[1] * xn[1] + xn[2] * xn[2] + xn[3] * xn[3];
;       if (gnext) { const f32x4 gv = *(const f32x4*)(gnext + c0 + j * 16); *(u32x2*)(stg + (i * 16 + l15) * STG_LD + j * 16 + quad * 4) = (u32x2){pk2(xn[0] * gv[0], xn[1] * gv[1]), pk2(xn[2] * gv[2], xn[3] * gv[3])}; }
;     }
;     s += __shfl_xor(s, 16); s += __shfl_xor(s, 32);
;     if (quad == 0) ((float*)(p.ws + O_SSQ))[(size_t)t * 16 + tn * 4 + wn] = s;
.LBB0_921:
	s_or_b64 exec, exec, s[16:17]
	v_or_b32_e32 v112, 16, v138
	s_waitcnt lgkmcnt(0)
	v_ashrrev_i32_e32 v113, 31, v112
	v_lshlrev_b64 v[114:115], 10, v[112:113]
	v_lshl_add_u64 v[114:115], v[114:115], 0, v[136:137]
	v_readlane_b32 s40, v241, 8
	v_lshlrev_b64 v[116:117], 2, v[114:115]
	v_readlane_b32 s41, v241, 9
	v_readlane_b32 s28, v241, 2
	v_readlane_b32 s30, v241, 4
	v_lshl_add_u64 v[114:115], s[40:41], 0, v[116:117]
	v_lshl_add_u64 v[212:213], v[212:213], 0, s[98:99]
	global_load_dwordx4 v[164:167], v[212:213], off
	global_load_dwordx4 v[168:171], v[212:213], off offset:64
	global_load_dwordx4 v[172:175], v[212:213], off offset:128
	global_load_dwordx4 v[192:195], v[212:213], off offset:192
	v_readlane_b32 s31, v241, 5
	s_and_b64 vcc, exec, s[0:1]
	v_readlane_b32 s42, v241, 10
	v_lshl_add_u64 v[116:117], s[30:31], 0, v[116:117]
	v_readlane_b32 s43, v241, 11
	v_readlane_b32 s44, v241, 12
	v_readlane_b32 s45, v241, 13
	v_readlane_b32 s46, v241, 14
	v_readlane_b32 s47, v241, 15
	v_readlane_b32 s48, v241, 16
	v_readlane_b32 s49, v241, 17
	v_readlane_b32 s50, v241, 18
	v_readlane_b32 s51, v241, 19
	v_readlane_b32 s52, v241, 20
	v_readlane_b32 s53, v241, 21
	v_readlane_b32 s54, v241, 22
	v_readlane_b32 s55, v241, 23
	v_readlane_b32 s29, v241, 3
	s_waitcnt vmcnt(8)
	v_pk_add_f32 v[110:111], v[110:111], v[198:199]
	v_pk_add_f32 v[108:109], v[108:109], v[196:197]
	global_store_dwordx4 v[116:117], v[108:111], off
	s_cbranch_vccnz .LBB0_923
	v_pk_mul_f32 v[124:125], v[110:111], v[178:179]
	v_pk_mul_f32 v[122:123], v[108:109], v[176:177]
	s_nop 0
	v_cvt_pk_bf16_f32 v122, v122, v123
	v_cvt_pk_bf16_f32 v123, v124, v125
	ds_write_b64 v133, v[122:123] offset:2304
.LBB0_923:
	s_and_b64 vcc, exec, s[0:1]
	v_pk_add_f32 v[106:107], v[106:107], v[202:203]
	v_pk_add_f32 v[104:105], v[104:105], v[200:201]
	global_store_dwordx4 v[116:117], v[104:107], off offset:64
	s_cbranch_vccnz .LBB0_925
	v_pk_mul_f32 v[124:125], v[106:107], v[182:183]
	v_pk_mul_f32 v[122:123], v[104:105], v[180:181]
	s_nop 0
	v_cvt_pk_bf16_f32 v122, v122, v123
	v_cvt_pk_bf16_f32 v123, v124, v125
	ds_write_b64 v133, v[122:123] offset:2336
.LBB0_925:
	s_and_b64 vcc, exec, s[0:1]
	v_pk_add_f32 v[102:103], v[102:103], v[206:207]
	v_pk_add_f32 v[100:101], v[100:101], v[204:205]
	global_store_dwordx4 v[116:117], v[100:103], off offset:128
	s_cbranch_vccnz .LBB0_927
	v_pk_mul_f32 v[124:125], v[102:103], v[186:187]
	v_pk_mul_f32 v[122:123], v[100:101], v[184:185]
	s_nop 0
	v_cvt_pk_bf16_f32 v122, v122, v123
	v_cvt_pk_bf16_f32 v123, v124, v125
	ds_write_b64 v133, v[122:123] offset:2368
.LBB0_927:
	s_and_b64 vcc, exec, s[0:1]
	v_pk_add_f32 v[98:99], v[98:99], v[210:211]
	v_pk_add_f32 v[96:97], v[96:97], v[208:209]
	global_store_dwordx4 v[116:117], v[96:99], off offset:192
	s_cbranch_vccnz .LBB0_929
	v_pk_mul_f32 v[116:117], v[98:99], v[190:191]
	v_pk_mul_f32 v[114:115], v[96:97], v[188:189]
	s_nop 0
	v_cvt_pk_bf16_f32 v114, v114, v115
	v_cvt_pk_bf16_f32 v115, v116, v117
	ds_write_b64 v133, v[114:115] offset:2400

; DI unsigned pk2(float lo, float hi) { f32x2 v = {lo, hi}; return __builtin_bit_cast(unsigned, __builtin_convertvector(v, bfx2)); }
; DI void resid_tile(const Params& p, const bf16_t* A, int K, const bf16_t* W, const float* xold, const float* gnext, int tm, int tn, bf16_t* smem) {
;     ...
; #pragma unroll
;   for (int i = 0; i < 8; ++i) {
;     const int t = tm * 256 + wm * 128 + i * 16 + l15, c0 = tn * 256 + wn * 64 + quad * 4; float s = 0.f;
; #pragma unroll
;     for (int j = 0; j < 4; ++j) {
;       const size_t off = (size_t)t * D_ + c0 + j * 16;
;       const f32x4 xn = *(const f32x4*)(xold + off) + acc[i][j];
;       *(f32x4*)(p.out + off) = xn;
;       s += xn[0] * xn[0] + xn[1] * xn[1] + xn[2] * xn[2] + xn[3] * xn[3];
;       if (gnext) { const f32x4 gv = *(const f32x4*)(gnext + c0 + j * 16); *(u32x2*)(stg + (i * 16 + l15) * STG_LD + j * 16 + quad * 4) = (u32x2){pk2(xn[0] * gv[0], xn[1] * gv[1]), pk2(xn[2] * gv[2], xn[3] * gv[3])}; }
;     }
;     s += __shfl_xor(s, 16); s += __shfl_xor(s, 32);
;     if (quad == 0) ((float*)(p.ws + O_SSQ))[(size_t)t * 16 + tn * 4 + wn] = s;
.LBB0_931:
	s_or_b64 exec, exec, s[16:17]
	v_or_b32_e32 v96, 32, v138
	s_waitcnt lgkmcnt(0)
	v_ashrrev_i32_e32 v97, 31, v96
	v_lshlrev_b64 v[98:99], 10, v[96:97]
	v_lshl_add_u64 v[98:99], v[98:99], 0, v[136:137]
	v_readlane_b32 s40, v241, 8
	v_lshlrev_b64 v[100:101], 2, v[98:99]
	v_readlane_b32 s41, v241, 9
	v_readlane_b32 s28, v241, 2
	v_readlane_b32 s30, v241, 4
	v_lshl_add_u64 v[98:99], s[40:41], 0, v[100:101]
	v_lshl_add_u64 v[212:213], v[212:213], 0, s[98:99]
	global_load_dwordx4 v[196:199], v[212:213], off
	global_load_dwordx4 v[200:203], v[212:213], off offset:64
	global_load_dwordx4 v[204:207], v[212:213], off offset:128
	global_load_dwordx4 v[208:211], v[212:213], off offset:192
	v_readlane_b32 s31, v241, 5
	s_and_b64 vcc, exec, s[0:1]
	v_readlane_b32 s42, v241, 10
	v_lshl_add_u64 v[100:101], s[30:31], 0, v[100:101]
	v_readlane_b32 s43, v241, 11
	v_readlane_b32 s44, v241, 12
	v_readlane_b32 s45, v241, 13
	v_readlane_b32 s46, v241, 14
	v_readlane_b32 s47, v241, 15
	v_readlane_b32 s48, v241, 16
	v_readlane_b32 s49, v241, 17
	v_readlane_b32 s50, v241, 18
	v_readlane_b32 s51, v241, 19
	v_readlane_b32 s52, v241, 20
	v_readlane_b32 s53, v241, 21
	v_readlane_b32 s54, v241, 22
	v_readlane_b32 s55, v241, 23
	v_readlane_b32 s29, v241, 3
	s_waitcnt vmcnt(8)
	v_pk_add_f32 v[94:95], v[94:95], v[166:167]
	v_pk_add_f32 v[92:93], v[92:93], v[164:165]
	global_store_dwordx4 v[100:101], v[92:95], off
	s_cbranch_vccnz .LBB0_933
	v_pk_mul_f32 v[104:105], v[94:95], v[178:179]
	v_pk_mul_f32 v[102:103], v[92:93], v[176:177]
	s_nop 0
	v_cvt_pk_bf16_f32 v102, v102, v103
	v_cvt_pk_bf16_f32 v103, v104, v105
	ds_write_b64 v133, v[102:103] offset:4608
.LBB0_933:
	s_and_b64 vcc, exec, s[0:1]
	v_pk_add_f32 v[90:91], v[90:91], v[170:171]
	v_pk_add_f32 v[88:89], v[88:89], v[168:169]
	global_store_dwordx4 v[100:101], v[88:91], off offset:64
	s_cbranch_vccnz .LBB0_935
	v_pk_mul_f32 v[104:105], v[90:91], v[182:183]
	v_pk_mul_f32 v[102:103], v[88:89], v[180:181]
	s_nop 0
	v_cvt_pk_bf16_f32 v102, v102, v103
	v_cvt_pk_bf16_f32 v103, v104, v105
	ds_write_b64 v133, v[102:103] offset:4640
.LBB0_935:
	s_and_b64 vcc, exec, s[0:1]
	v_pk_add_f32 v[86:87], v[86:87], v[174:175]
	v_pk_add_f32 v[84:85], v[84:85], v[172:173]
	global_store_dwordx4 v[100:101], v[84:87], off offset:128
	s_cbranch_vccnz .LBB0_937
	v_pk_mul_f32 v[104:105], v[86:87], v[186:187]
	v_pk_mul_f32 v[102:103], v[84:85], v[184:185]
	s_nop 0
	v_cvt_pk_bf16_f32 v102, v102, v103
	v_cvt_pk_bf16_f32 v103, v104, v105
	ds_write_b64 v133, v[102:103] offset:4672
.LBB0_937:
	s_and_b64 vcc, exec, s[0:1]
	v_pk_add_f32 v[82:83], v[82:83], v[194:195]
	v_pk_add_f32 v[80:81], v[80:81], v[192:193]
	global_store_dwordx4 v[100:101], v[80:83], off offset:192
	s_cbranch_vccnz .LBB0_939
	v_pk_mul_f32 v[100:101], v[82:83], v[190:191]
	v_pk_mul_f32 v[98:99], v[80:81], v[188:189]
	s_nop 0
	v_cvt_pk_bf16_f32 v98, v98, v99
	v_cvt_pk_bf16_f32 v99, v100, v101
	ds_write_b64 v133, v[98:99] offset:4704

; DI unsigned pk2(float lo, float hi) { f32x2 v = {lo, hi}; return __builtin_bit_cast(unsigned, __builtin_convertvector(v, bfx2)); }
; DI void resid_tile(const Params& p, const bf16_t* A, int K, const bf16_t* W, const float* xold, const float* gnext, int tm, int tn, bf16_t* smem) {
;     ...
; #pragma unroll
;   for (int i = 0; i < 8; ++i) {
;     const int t = tm * 256 + wm * 128 + i * 16 + l15, c0 = tn * 256 + wn * 64 + quad * 4; float s = 0.f;
; #pragma unroll
;     for (int j = 0; j < 4; ++j) {
;       const size_t off = (size_t)t * D_ + c0 + j * 16;
;       const f32x4 xn = *(const f32x4*)(xold + off) + acc[i][j];
;       *(f32x4*)(p.out + off) = xn;
;       s += xn[0] * xn[0] + xn[1] * xn[1] + xn[2] * xn[2] + xn[3] * xn[3];
;       if (gnext) { const f32x4 gv = *(const f32x4*)(gnext + c0 + j * 16); *(u32x2*)(stg + (i * 16 + l15) * STG_LD + j * 16 + quad * 4) = (u32x2){pk2(xn[0] * gv[0], xn[1] * gv[1]), pk2(xn[2] * gv[2], xn[3] * gv[3])}; }
;     }
;     s += __shfl_xor(s, 16); s += __shfl_xor(s, 32);
;     if (quad == 0) ((float*)(p.ws + O_SSQ))[(size_t)t * 16 + tn * 4 + wn] = s;
.LBB0_941:
	s_or_b64 exec, exec, s[16:17]
	v_or_b32_e32 v80, 48, v138
	s_waitcnt lgkmcnt(0)
	v_ashrrev_i32_e32 v81, 31, v80
	v_lshlrev_b64 v[82:83], 10, v[80:81]
	v_lshl_add_u64 v[82:83], v[82:83], 0, v[136:137]
	v_readlane_b32 s40, v241, 8
	v_lshlrev_b64 v[84:85], 2, v[82:83]
	v_readlane_b32 s41, v241, 9
	v_readlane_b32 s28, v241, 2
	v_readlane_b32 s30, v241, 4
	v_lshl_add_u64 v[82:83], s[40:41], 0, v[84:85]
	v_lshl_add_u64 v[212:213], v[212:213], 0, s[98:99]
	global_load_dwordx4 v[164:167], v[212:213], off
	global_load_dwordx4 v[168:171], v[212:213], off offset:64
	global_load_dwordx4 v[172:175], v[212:213], off offset:128
	global_load_dwordx4 v[192:195], v[212:213], off offset:192
	v_readlane_b32 s31, v241, 5
	s_and_b64 vcc, exec, s[0:1]
	v_readlane_b32 s42, v241, 10
	v_lshl_add_u64 v[84:85], s[30:31], 0, v[84:85]
	v_readlane_b32 s43, v241, 11
	v_readlane_b32 s44, v241, 12
	v_readlane_b32 s45, v241, 13
	v_readlane_b32 s46, v241, 14
	v_readlane_b32 s47, v241, 15
	v_readlane_b32 s48, v241, 16
	v_readlane_b32 s49, v241, 17
	v_readlane_b32 s50, v241, 18
	v_readlane_b32 s51, v241, 19
	v_readlane_b32 s52, v241, 20
	v_readlane_b32 s53, v241, 21
	v_readlane_b32 s54, v241, 22
	v_readlane_b32 s55, v241, 23
	v_readlane_b32 s29, v241, 3
	s_waitcnt vmcnt(8)
	v_pk_add_f32 v[78:79], v[78:79], v[198:199]
	v_pk_add_f32 v[76:77], v[76:77], v[196:197]
	global_store_dwordx4 v[84:85], v[76:79], off
	s_cbranch_vccnz .LBB0_943
	v_pk_mul_f32 v[88:89], v[78:79], v[178:179]
	v_pk_mul_f32 v[86:87], v[76:77], v[176:177]
	s_nop 0
	v_cvt_pk_bf16_f32 v86, v86, v87
	v_cvt_pk_bf16_f32 v87, v88, v89
	ds_write_b64 v133, v[86:87] offset:6912
.LBB0_943:
	s_and_b64 vcc, exec, s[0:1]
	v_pk_add_f32 v[74:75], v[74:75], v[202:203]
	v_pk_add_f32 v[72:73], v[72:73], v[200:201]
	global_store_dwordx4 v[84:85], v[72:75], off offset:64
	s_cbranch_vccnz .LBB0_945
	v_pk_mul_f32 v[88:89], v[74:75], v[182:183]
	v_pk_mul_f32 v[86:87], v[72:73], v[180:181]
	s_nop 0
	v_cvt_pk_bf16_f32 v86, v86, v87
	v_cvt_pk_bf16_f32 v87, v88, v89
	ds_write_b64 v133, v[86:87] offset:6944
.LBB0_945:
	s_and_b64 vcc, exec, s[0:1]
	v_pk_add_f32 v[70:71], v[70:71], v[206:207]
	v_pk_add_f32 v[68:69], v[68:69], v[204:205]
	global_store_dwordx4 v[84:85], v[68:71], off offset:128
	s_cbranch_vccnz .LBB0_947
	v_pk_mul_f32 v[88:89], v[70:71], v[186:187]
	v_pk_mul_f32 v[86:87], v[68:69], v[184:185]
	s_nop 0
	v_cvt_pk_bf16_f32 v86, v86, v87
	v_cvt_pk_bf16_f32 v87, v88, v89
	ds_write_b64 v133, v[86:87] offset:6976
.LBB0_947:
	s_and_b64 vcc, exec, s[0:1]
	v_pk_add_f32 v[66:67], v[66:67], v[210:211]
	v_pk_add_f32 v[64:65], v[64:65], v[208:209]
	global_store_dwordx4 v[84:85], v[64:67], off offset:192
	s_cbranch_vccnz .LBB0_949
	v_pk_mul_f32 v[84:85], v[66:67], v[190:191]
	v_pk_mul_f32 v[82:83], v[64:65], v[188:189]
	s_nop 0
	v_cvt_pk_bf16_f32 v82, v82, v83
	v_cvt_pk_bf16_f32 v83, v84, v85
	ds_write_b64 v133, v[82:83] offset:7008

; DI unsigned pk2(float lo, float hi) { f32x2 v = {lo, hi}; return __builtin_bit_cast(unsigned, __builtin_convertvector(v, bfx2)); }
; DI void resid_tile(const Params& p, const bf16_t* A, int K, const bf16_t* W, const float* xold, const float* gnext, int tm, int tn, bf16_t* smem) {
;     ...
; #pragma unroll
;   for (int i = 0; i < 8; ++i) {
;     const int t = tm * 256 + wm * 128 + i * 16 + l15, c0 = tn * 256 + wn * 64 + quad * 4; float s = 0.f;
; #pragma unroll
;     for (int j = 0; j < 4; ++j) {
;       const size_t off = (size_t)t * D_ + c0 + j * 16;
;       const f32x4 xn = *(const f32x4*)(xold + off) + acc[i][j];
;       *(f32x4*)(p.out + off) = xn;
;       s += xn[0] * xn[0] + xn[1] * xn[1] + xn[2] * xn[2] + xn[3] * xn[3];
;       if (gnext) { const f32x4 gv = *(const f32x4*)(gnext + c0 + j * 16); *(u32x2*)(stg + (i * 16 + l15) * STG_LD + j * 16 + quad * 4) = (u32x2){pk2(xn[0] * gv[0], xn[1] * gv[1]), pk2(xn[2] * gv[2], xn[3] * gv[3])}; }
;     }
;     s += __shfl_xor(s, 16); s += __shfl_xor(s, 32);
;     if (quad == 0) ((float*)(p.ws + O_SSQ))[(size_t)t * 16 + tn * 4 + wn] = s;
.LBB0_951:
	s_or_b64 exec, exec, s[16:17]
	v_or_b32_e32 v64, 64, v138
	s_waitcnt lgkmcnt(0)
	v_ashrrev_i32_e32 v65, 31, v64
	v_lshlrev_b64 v[66:67], 10, v[64:65]
	v_lshl_add_u64 v[66:67], v[66:67], 0, v[136:137]
	v_readlane_b32 s40, v241, 8
	v_lshlrev_b64 v[68:69], 2, v[66:67]
	v_readlane_b32 s41, v241, 9
	v_readlane_b32 s28, v241, 2
	v_readlane_b32 s30, v241, 4
	v_lshl_add_u64 v[66:67], s[40:41], 0, v[68:69]
	v_lshl_add_u64 v[212:213], v[212:213], 0, s[98:99]
	global_load_dwordx4 v[196:199], v[212:213], off
	global_load_dwordx4 v[200:203], v[212:213], off offset:64
	global_load_dwordx4 v[204:207], v[212:213], off offset:128
	global_load_dwordx4 v[208:211], v[212:213], off offset:192
	v_readlane_b32 s31, v241, 5
	s_and_b64 vcc, exec, s[0:1]
	v_readlane_b32 s42, v241, 10
	v_lshl_add_u64 v[68:69], s[30:31], 0, v[68:69]
	v_readlane_b32 s43, v241, 11
	v_readlane_b32 s44, v241, 12
	v_readlane_b32 s45, v241, 13
	v_readlane_b32 s46, v241, 14
	v_readlane_b32 s47, v241, 15
	v_readlane_b32 s48, v241, 16
	v_readlane_b32 s49, v241, 17
	v_readlane_b32 s50, v241, 18
	v_readlane_b32 s51, v241, 19
	v_readlane_b32 s52, v241, 20
	v_readlane_b32 s53, v241, 21
	v_readlane_b32 s54, v241, 22
	v_readlane_b32 s55, v241, 23
	v_readlane_b32 s29, v241, 3
	s_waitcnt vmcnt(8)
	v_pk_add_f32 v[62:63], v[62:63], v[166:167]
	v_pk_add_f32 v[60:61], v[60:61], v[164:165]
	global_store_dwordx4 v[68:69], v[60:63], off
	s_cbranch_vccnz .LBB0_953
	v_pk_mul_f32 v[72:73], v[62:63], v[178:179]
	v_pk_mul_f32 v[70:71], v[60:61], v[176:177]
	s_nop 0
	v_cvt_pk_bf16_f32 v70, v70, v71
	v_cvt_pk_bf16_f32 v71, v72, v73
	ds_write_b64 v133, v[70:71] offset:9216
.LBB0_953:
	s_and_b64 vcc, exec, s[0:1]
	v_pk_add_f32 v[58:59], v[58:59], v[170:171]
	v_pk_add_f32 v[56:57], v[56:57], v[168:169]
	global_store_dwordx4 v[68:69], v[56:59], off offset:64
	s_cbranch_vccnz .LBB0_955
	v_pk_mul_f32 v[72:73], v[58:59], v[182:183]
	v_pk_mul_f32 v[70:71], v[56:57], v[180:181]
	s_nop 0
	v_cvt_pk_bf16_f32 v70, v70, v71
	v_cvt_pk_bf16_f32 v71, v72, v73
	ds_write_b64 v133, v[70:71] offset:9248
.LBB0_955:
	s_and_b64 vcc, exec, s[0:1]
	v_pk_add_f32 v[54:55], v[54:55], v[174:175]
	v_pk_add_f32 v[52:53], v[52:53], v[172:173]
	global_store_dwordx4 v[68:69], v[52:55], off offset:128
	s_cbranch_vccnz .LBB0_957
	v_pk_mul_f32 v[72:73], v[54:55], v[186:187]
	v_pk_mul_f32 v[70:71], v[52:53], v[184:185]
	s_nop 0
	v_cvt_pk_bf16_f32 v70, v70, v71
	v_cvt_pk_bf16_f32 v71, v72, v73
	ds_write_b64 v133, v[70:71] offset:9280
.LBB0_957:
	s_and_b64 vcc, exec, s[0:1]
	v_pk_add_f32 v[50:51], v[50:51], v[194:195]
	v_pk_add_f32 v[48:49], v[48:49], v[192:193]
	global_store_dwordx4 v[68:69], v[48:51], off offset:192
	s_cbranch_vccnz .LBB0_959
	v_pk_mul_f32 v[68:69], v[50:51], v[190:191]
	v_pk_mul_f32 v[66:67], v[48:49], v[188:189]
	s_nop 0
	v_cvt_pk_bf16_f32 v66, v66, v67
	v_cvt_pk_bf16_f32 v67, v68, v69
	ds_write_b64 v133, v[66:67] offset:9312

; DI unsigned pk2(float lo, float hi) { f32x2 v = {lo, hi}; return __builtin_bit_cast(unsigned, __builtin_convertvector(v, bfx2)); }
; DI void resid_tile(const Params& p, const bf16_t* A, int K, const bf16_t* W, const float* xold, const float* gnext, int tm, int tn, bf16_t* smem) {
;     ...
; #pragma unroll
;   for (int i = 0; i < 8; ++i) {
;     const int t = tm * 256 + wm * 128 + i * 16 + l15, c0 = tn * 256 + wn * 64 + quad * 4; float s = 0.f;
; #pragma unroll
;     for (int j = 0; j < 4; ++j) {
;       const size_t off = (size_t)t * D_ + c0 + j * 16;
;       const f32x4 xn = *(const f32x4*)(xold + off) + acc[i][j];
;       *(f32x4*)(p.out + off) = xn;
;       s += xn[0] * xn[0] + xn[1] * xn[1] + xn[2] * xn[2] + xn[3] * xn[3];
;       if (gnext) { const f32x4 gv = *(const f32x4*)(gnext + c0 + j * 16); *(u32x2*)(stg + (i * 16 + l15) * STG_LD + j * 16 + quad * 4) = (u32x2){pk2(xn[0] * gv[0], xn[1] * gv[1]), pk2(xn[2] * gv[2], xn[3] * gv[3])}; }
;     }
;     s += __shfl_xor(s, 16); s += __shfl_xor(s, 32);
;     if (quad == 0) ((float*)(p.ws + O_SSQ))[(size_t)t * 16 + tn * 4 + wn] = s;
.LBB0_961:
	s_or_b64 exec, exec, s[16:17]
	v_or_b32_e32 v48, 0x50, v138
	s_waitcnt lgkmcnt(0)
	v_ashrrev_i32_e32 v49, 31, v48
	v_lshlrev_b64 v[50:51], 10, v[48:49]
	v_lshl_add_u64 v[50:51], v[50:51], 0, v[136:137]
	v_readlane_b32 s40, v241, 8
	v_lshlrev_b64 v[52:53], 2, v[50:51]
	v_readlane_b32 s41, v241, 9
	v_readlane_b32 s28, v241, 2
	v_readlane_b32 s30, v241, 4
	v_lshl_add_u64 v[50:51], s[40:41], 0, v[52:53]
	v_lshl_add_u64 v[212:213], v[212:213], 0, s[98:99]
	global_load_dwordx4 v[164:167], v[212:213], off
	global_load_dwordx4 v[168:171], v[212:213], off offset:64
	global_load_dwordx4 v[172:175], v[212:213], off offset:128
	global_load_dwordx4 v[192:195], v[212:213], off offset:192
	v_readlane_b32 s31, v241, 5
	s_and_b64 vcc, exec, s[0:1]
	v_readlane_b32 s42, v241, 10
	v_lshl_add_u64 v[52:53], s[30:31], 0, v[52:53]
	v_readlane_b32 s43, v241, 11
	v_readlane_b32 s44, v241, 12
	v_readlane_b32 s45, v241, 13
	v_readlane_b32 s46, v241, 14
	v_readlane_b32 s47, v241, 15
	v_readlane_b32 s48, v241, 16
	v_readlane_b32 s49, v241, 17
	v_readlane_b32 s50, v241, 18
	v_readlane_b32 s51, v241, 19
	v_readlane_b32 s52, v241, 20
	v_readlane_b32 s53, v241, 21
	v_readlane_b32 s54, v241, 22
	v_readlane_b32 s55, v241, 23
	v_readlane_b32 s29, v241, 3
	s_waitcnt vmcnt(8)
	v_pk_add_f32 v[46:47], v[46:47], v[198:199]
	v_pk_add_f32 v[44:45], v[44:45], v[196:197]
	global_store_dwordx4 v[52:53], v[44:47], off
	s_cbranch_vccnz .LBB0_963
	v_pk_mul_f32 v[56:57], v[46:47], v[178:179]
	v_pk_mul_f32 v[54:55], v[44:45], v[176:177]
	s_nop 0
	v_cvt_pk_bf16_f32 v54, v54, v55
	v_cvt_pk_bf16_f32 v55, v56, v57
	ds_write_b64 v133, v[54:55] offset:11520
.LBB0_963:
	s_and_b64 vcc, exec, s[0:1]
	v_pk_add_f32 v[42:43], v[42:43], v[202:203]
	v_pk_add_f32 v[40:41], v[40:41], v[200:201]
	global_store_dwordx4 v[52:53], v[40:43], off offset:64
	s_cbranch_vccnz .LBB0_965
	v_pk_mul_f32 v[56:57], v[42:43], v[182:183]
	v_pk_mul_f32 v[54:55], v[40:41], v[180:181]
	s_nop 0
	v_cvt_pk_bf16_f32 v54, v54, v55
	v_cvt_pk_bf16_f32 v55, v56, v57
	ds_write_b64 v133, v[54:55] offset:11552
.LBB0_965:
	s_and_b64 vcc, exec, s[0:1]
	v_pk_add_f32 v[38:39], v[38:39], v[206:207]
	v_pk_add_f32 v[36:37], v[36:37], v[204:205]
	global_store_dwordx4 v[52:53], v[36:39], off offset:128
	s_cbranch_vccnz .LBB0_967
	v_pk_mul_f32 v[56:57], v[38:39], v[186:187]
	v_pk_mul_f32 v[54:55], v[36:37], v[184:185]
	s_nop 0
	v_cvt_pk_bf16_f32 v54, v54, v55
	v_cvt_pk_bf16_f32 v55, v56, v57
	ds_write_b64 v133, v[54:55] offset:11584
.LBB0_967:
	s_and_b64 vcc, exec, s[0:1]
	v_pk_add_f32 v[34:35], v[34:35], v[210:211]
	v_pk_add_f32 v[32:33], v[32:33], v[208:209]
	global_store_dwordx4 v[52:53], v[32:35], off offset:192
	s_cbranch_vccnz .LBB0_969
	v_pk_mul_f32 v[52:53], v[34:35], v[190:191]
	v_pk_mul_f32 v[50:51], v[32:33], v[188:189]
	s_nop 0
	v_cvt_pk_bf16_f32 v50, v50, v51
	v_cvt_pk_bf16_f32 v51, v52, v53
	ds_write_b64 v133, v[50:51] offset:11616

; DI unsigned pk2(float lo, float hi) { f32x2 v = {lo, hi}; return __builtin_bit_cast(unsigned, __builtin_convertvector(v, bfx2)); }
; DI void resid_tile(const Params& p, const bf16_t* A, int K, const bf16_t* W, const float* xold, const float* gnext, int tm, int tn, bf16_t* smem) {
;     ...
; #pragma unroll
;   for (int i = 0; i < 8; ++i) {
;     const int t = tm * 256 + wm * 128 + i * 16 + l15, c0 = tn * 256 + wn * 64 + quad * 4; float s = 0.f;
; #pragma unroll
;     for (int j = 0; j < 4; ++j) {
;       const size_t off = (size_t)t * D_ + c0 + j * 16;
;       const f32x4 xn = *(const f32x4*)(xold + off) + acc[i][j];
;       *(f32x4*)(p.out + off) = xn;
;       s += xn[0] * xn[0] + xn[1] * xn[1] + xn[2] * xn[2] + xn[3] * xn[3];
;       if (gnext) { const f32x4 gv = *(const f32x4*)(gnext + c0 + j * 16); *(u32x2*)(stg + (i * 16 + l15) * STG_LD + j * 16 + quad * 4) = (u32x2){pk2(xn[0] * gv[0], xn[1] * gv[1]), pk2(xn[2] * gv[2], xn[3] * gv[3])}; }
;     }
;     s += __shfl_xor(s, 16); s += __shfl_xor(s, 32);
;     if (quad == 0) ((float*)(p.ws + O_SSQ))[(size_t)t * 16 + tn * 4 + wn] = s;
.LBB0_971:
	s_or_b64 exec, exec, s[16:17]
	v_or_b32_e32 v32, 0x60, v138
	s_waitcnt lgkmcnt(0)
	v_ashrrev_i32_e32 v33, 31, v32
	v_lshlrev_b64 v[34:35], 10, v[32:33]
	v_lshl_add_u64 v[34:35], v[34:35], 0, v[136:137]
	v_readlane_b32 s40, v241, 8
	v_lshlrev_b64 v[36:37], 2, v[34:35]
	v_readlane_b32 s41, v241, 9
	v_readlane_b32 s28, v241, 2
	v_readlane_b32 s30, v241, 4
	v_lshl_add_u64 v[34:35], s[40:41], 0, v[36:37]
	v_lshl_add_u64 v[212:213], v[212:213], 0, s[98:99]
	global_load_dwordx4 v[196:199], v[212:213], off
	global_load_dwordx4 v[200:203], v[212:213], off offset:64
	global_load_dwordx4 v[204:207], v[212:213], off offset:128
	global_load_dwordx4 v[208:211], v[212:213], off offset:192
	v_readlane_b32 s31, v241, 5
	s_and_b64 vcc, exec, s[0:1]
	v_readlane_b32 s42, v241, 10
	v_lshl_add_u64 v[36:37], s[30:31], 0, v[36:37]
	v_readlane_b32 s43, v241, 11
	v_readlane_b32 s44, v241, 12
	v_readlane_b32 s45, v241, 13
	v_readlane_b32 s46, v241, 14
	v_readlane_b32 s47, v241, 15
	v_readlane_b32 s48, v241, 16
	v_readlane_b32 s49, v241, 17
	v_readlane_b32 s50, v241, 18
	v_readlane_b32 s51, v241, 19
	v_readlane_b32 s52, v241, 20
	v_readlane_b32 s53, v241, 21
	v_readlane_b32 s54, v241, 22
	v_readlane_b32 s55, v241, 23
	v_readlane_b32 s29, v241, 3
	s_waitcnt vmcnt(8)
	v_pk_add_f32 v[30:31], v[30:31], v[166:167]
	v_pk_add_f32 v[28:29], v[28:29], v[164:165]
	global_store_dwordx4 v[36:37], v[28:31], off
	s_cbranch_vccnz .LBB0_973
	v_pk_mul_f32 v[40:41], v[30:31], v[178:179]
	v_pk_mul_f32 v[38:39], v[28:29], v[176:177]
	s_nop 0
	v_cvt_pk_bf16_f32 v38, v38, v39
	v_cvt_pk_bf16_f32 v39, v40, v41
	ds_write_b64 v133, v[38:39] offset:13824
.LBB0_973:
	s_and_b64 vcc, exec, s[0:1]
	v_pk_add_f32 v[26:27], v[26:27], v[170:171]
	v_pk_add_f32 v[24:25], v[24:25], v[168:169]
	global_store_dwordx4 v[36:37], v[24:27], off offset:64
	s_cbranch_vccnz .LBB0_975
	v_pk_mul_f32 v[40:41], v[26:27], v[182:183]
	v_pk_mul_f32 v[38:39], v[24:25], v[180:181]
	s_nop 0
	v_cvt_pk_bf16_f32 v38, v38, v39
	v_cvt_pk_bf16_f32 v39, v40, v41
	ds_write_b64 v133, v[38:39] offset:13856
.LBB0_975:
	s_and_b64 vcc, exec, s[0:1]
	v_pk_add_f32 v[22:23], v[22:23], v[174:175]
	v_pk_add_f32 v[20:21], v[20:21], v[172:173]
	global_store_dwordx4 v[36:37], v[20:23], off offset:128
	s_cbranch_vccnz .LBB0_977
	v_pk_mul_f32 v[40:41], v[22:23], v[186:187]
	v_pk_mul_f32 v[38:39], v[20:21], v[184:185]
	s_nop 0
	v_cvt_pk_bf16_f32 v38, v38, v39
	v_cvt_pk_bf16_f32 v39, v40, v41
	ds_write_b64 v133, v[38:39] offset:13888
.LBB0_977:
	s_and_b64 vcc, exec, s[0:1]
	v_pk_add_f32 v[18:19], v[18:19], v[194:195]
	v_pk_add_f32 v[16:17], v[16:17], v[192:193]
	global_store_dwordx4 v[36:37], v[16:19], off offset:192
	s_cbranch_vccnz .LBB0_979
	v_pk_mul_f32 v[36:37], v[18:19], v[190:191]
	v_pk_mul_f32 v[34:35], v[16:17], v[188:189]
	s_nop 0
	v_cvt_pk_bf16_f32 v34, v34, v35
	v_cvt_pk_bf16_f32 v35, v36, v37
	ds_write_b64 v133, v[34:35] offset:13920

; DI unsigned pk2(float lo, float hi) { f32x2 v = {lo, hi}; return __builtin_bit_cast(unsigned, __builtin_convertvector(v, bfx2)); }
; DI void resid_tile(const Params& p, const bf16_t* A, int K, const bf16_t* W, const float* xold, const float* gnext, int tm, int tn, bf16_t* smem) {
;     ...
; #pragma unroll
;   for (int i = 0; i < 8; ++i) {
;     const int t = tm * 256 + wm * 128 + i * 16 + l15, c0 = tn * 256 + wn * 64 + quad * 4; float s = 0.f;
; #pragma unroll
;     for (int j = 0; j < 4; ++j) {
;       const size_t off = (size_t)t * D_ + c0 + j * 16;
;       const f32x4 xn = *(const f32x4*)(xold + off) + acc[i][j];
;       *(f32x4*)(p.out + off) = xn;
;       s += xn[0] * xn[0] + xn[1] * xn[1] + xn[2] * xn[2] + xn[3] * xn[3];
;       if (gnext) { const f32x4 gv = *(const f32x4*)(gnext + c0 + j * 16); *(u32x2*)(stg + (i * 16 + l15) * STG_LD + j * 16 + quad * 4) = (u32x2){pk2(xn[0] * gv[0], xn[1] * gv[1]), pk2(xn[2] * gv[2], xn[3] * gv[3])}; }
;     }
;     s += __shfl_xor(s, 16); s += __shfl_xor(s, 32);
;     if (quad == 0) ((float*)(p.ws + O_SSQ))[(size_t)t * 16 + tn * 4 + wn] = s;
.LBB0_981:
	s_or_b64 exec, exec, s[16:17]
	v_or_b32_e32 v16, 0x70, v138
	s_waitcnt lgkmcnt(0)
	v_ashrrev_i32_e32 v17, 31, v16
	v_lshlrev_b64 v[18:19], 10, v[16:17]
	v_lshl_add_u64 v[18:19], v[18:19], 0, v[136:137]
	v_readlane_b32 s40, v241, 8
	v_lshlrev_b64 v[20:21], 2, v[18:19]
	v_readlane_b32 s41, v241, 9
	v_readlane_b32 s28, v241, 2
	v_readlane_b32 s30, v241, 4
	v_lshl_add_u64 v[18:19], s[40:41], 0, v[20:21]
	v_readlane_b32 s31, v241, 5
	s_and_b64 vcc, exec, s[0:1]
	v_readlane_b32 s42, v241, 10
	v_lshl_add_u64 v[20:21], s[30:31], 0, v[20:21]
	v_readlane_b32 s43, v241, 11
	v_readlane_b32 s44, v241, 12
	v_readlane_b32 s45, v241, 13
	v_readlane_b32 s46, v241, 14
	v_readlane_b32 s47, v241, 15
	v_readlane_b32 s48, v241, 16
	v_readlane_b32 s49, v241, 17
	v_readlane_b32 s50, v241, 18
	v_readlane_b32 s51, v241, 19
	v_readlane_b32 s52, v241, 20
	v_readlane_b32 s53, v241, 21
	v_readlane_b32 s54, v241, 22
	v_readlane_b32 s55, v241, 23
	v_readlane_b32 s29, v241, 3
	s_waitcnt vmcnt(4)
	v_pk_add_f32 v[10:11], v[10:11], v[198:199]
	v_pk_add_f32 v[8:9], v[8:9], v[196:197]
	global_store_dwordx4 v[20:21], v[8:11], off
	s_cbranch_vccnz .LBB0_983
	v_pk_mul_f32 v[24:25], v[10:11], v[178:179]
	v_pk_mul_f32 v[22:23], v[8:9], v[176:177]
	s_nop 0
	v_cvt_pk_bf16_f32 v22, v22, v23
	v_cvt_pk_bf16_f32 v23, v24, v25
	ds_write_b64 v133, v[22:23] offset:16128
.LBB0_983:
	s_and_b64 vcc, exec, s[0:1]
	v_pk_add_f32 v[6:7], v[6:7], v[202:203]
	v_pk_add_f32 v[4:5], v[4:5], v[200:201]
	global_store_dwordx4 v[20:21], v[4:7], off offset:64
	s_cbranch_vccnz .LBB0_985
	v_pk_mul_f32 v[24:25], v[6:7], v[182:183]
	v_pk_mul_f32 v[22:23], v[4:5], v[180:181]
	s_nop 0
	v_cvt_pk_bf16_f32 v22, v22, v23
	v_cvt_pk_bf16_f32 v23, v24, v25
	ds_write_b64 v133, v[22:23] offset:16160
.LBB0_985:
	s_and_b64 vcc, exec, s[0:1]
	v_pk_add_f32 v[2:3], v[2:3], v[206:207]
	v_pk_add_f32 v[0:1], v[0:1], v[204:205]
	global_store_dwordx4 v[20:21], v[0:3], off offset:128
	s_cbranch_vccnz .LBB0_987
	v_pk_mul_f32 v[24:25], v[2:3], v[186:187]
	v_pk_mul_f32 v[22:23], v[0:1], v[184:185]
	s_nop 0
	v_cvt_pk_bf16_f32 v22, v22, v23
	v_cvt_pk_bf16_f32 v23, v24, v25
	ds_write_b64 v133, v[22:23] offset:16192
.LBB0_987:
	s_and_b64 vcc, exec, s[0:1]
	v_pk_add_f32 v[14:15], v[14:15], v[210:211]
	v_pk_add_f32 v[12:13], v[12:13], v[208:209]
	global_store_dwordx4 v[20:21], v[12:15], off offset:192
	s_cbranch_vccnz .LBB0_989
	v_pk_mul_f32 v[20:21], v[14:15], v[190:191]
	v_pk_mul_f32 v[18:19], v[12:13], v[188:189]
	s_nop 0
	v_cvt_pk_bf16_f32 v18, v18, v19
	v_cvt_pk_bf16_f32 v19, v20, v21
	ds_write_b64 v133, v[18:19] offset:16224

; DI int TIDX() { int t = (int)threadIdx.x; asm volatile("" : "+v"(t)); return t; }
; DI unsigned pk2(float lo, float hi) { f32x2 v = {lo, hi}; return __builtin_bit_cast(unsigned, __builtin_convertvector(v, bfx2)); }
; DI void resid_tile(const Params& p, const bf16_t* A, int K, const bf16_t* W, const float* xold, const float* gnext, int tm, int tn, bf16_t* smem) {
;     ...
;   const int lane = TIDX() & 63, wid = TIDX() >> 6, wm = wid >> 2, wn = wid & 3, l15 = lane & 15, quad = lane >> 4;
;   bf16_t* stg = smem + wid * STG_WAVE;
; #pragma unroll
;   for (int i = 0; i < 8; ++i) {
;     const int t = tm * 256 + wm * 128 + i * 16 + l15, c0 = tn * 256 + wn * 64 + quad * 4; float s = 0.f;
; #pragma unroll
;     for (int j = 0; j < 4; ++j) {
;       const size_t off = (size_t)t * D_ + c0 + j * 16;
;       const f32x4 xn = *(const f32x4*)(xold + off) + acc[i][j];
;       *(f32x4*)(p.out + off) = xn;
;       s += xn[0] * xn[0] + xn[1] * xn[1] + xn[2] * xn[2] + xn[3] * xn[3];
;       if (gnext) { const f32x4 gv = *(const f32x4*)(gnext + c0 + j * 16); *(u32x2*)(stg + (i * 16 + l15) * STG_LD + j * 16 + quad * 4) = (u32x2){pk2(xn[0] * gv[0], xn[1] * gv[1]), pk2(xn[2] * gv[2], xn[3] * gv[3])}; }
;     }
.Lgm13_exit:
	v_mfma_f32_16x16x32_bf16 v[28:31], v[178:181], v[242:245], v[28:31]
	v_mfma_f32_16x16x32_bf16 v[8:11], v[178:181], v[246:249], v[8:11]
	v_mfma_f32_16x16x32_bf16 v[24:27], v[182:185], v[242:245], v[24:27]
	v_mfma_f32_16x16x32_bf16 v[4:7], v[182:185], v[246:249], v[4:7]
	v_mfma_f32_16x16x32_bf16 v[20:23], v[186:189], v[242:245], v[20:23]
	v_mfma_f32_16x16x32_bf16 v[0:3], v[186:189], v[246:249], v[0:3]
	v_mfma_f32_16x16x32_bf16 v[16:19], v[190:193], v[242:245], v[16:19]
	v_mfma_f32_16x16x32_bf16 v[12:15], v[190:193], v[246:249], v[12:15]
	s_nop 7
	s_waitcnt vmcnt(0)
	v_mov_b32_e32 v141, v220
	v_mov_b32_e32 v112, v220
	s_lshl_b32 s12, s14, 8
	v_ashrrev_i32_e32 v118, 6, v112
	v_ashrrev_i32_e32 v112, 1, v112
	v_and_b32_e32 v112, 0xffffff80, v112
	v_and_b32_e32 v140, 3, v118
	v_and_b32_e32 v119, 15, v141
	v_lshl_add_u32 v128, s0, 8, v112
	v_lshrrev_b32_e32 v112, 2, v141
	v_or_b32_e32 v134, v128, v119
	v_lshlrev_b32_e32 v138, 6, v140
	v_and_b32_e32 v120, 12, v112
	v_or3_b32 v132, v120, s12, v138
	v_ashrrev_i32_e32 v135, 31, v134
	v_readlane_b32 s0, v241, 2
	v_ashrrev_i32_e32 v133, 31, v132
	v_lshlrev_b64 v[112:113], 12, v[134:135]
	v_readlane_b32 s2, v241, 4
	v_readlane_b32 s3, v241, 5
	v_lshlrev_b64 v[116:117], 2, v[132:133]
	v_mul_lo_u32 v139, v118, s25
	v_lshl_add_u64 v[112:113], s[2:3], 0, v[112:113]
	v_lshl_add_u64 v[136:137], v[112:113], 0, v[116:117]
	global_load_dwordx4 v[164:167], v[136:137], off
	global_load_dwordx4 v[168:171], v[136:137], off offset:64
	global_load_dwordx4 v[172:175], v[136:137], off offset:128
	global_load_dwordx4 v[192:195], v[136:137], off offset:192
	s_mov_b32 s98, 0x10000
	s_mov_b32 s99, 0
	v_lshl_add_u64 v[212:213], v[136:137], 0, s[98:99]
	global_load_dwordx4 v[196:199], v[212:213], off
	global_load_dwordx4 v[200:203], v[212:213], off offset:64
	global_load_dwordx4 v[204:207], v[212:213], off offset:128
	global_load_dwordx4 v[208:211], v[212:213], off offset:192
	v_readlane_b32 s1, v241, 3
	v_cndmask_b32_e64 v121, 0, 1, s[6:7]
	v_mul_u32_u24_e32 v118, 0x90, v119
	v_lshl_or_b32 v119, v120, 1, v139
	v_cmp_ne_u32_e64 s[0:1], 1, v121
	s_andn2_b64 vcc, exec, s[6:7]
	v_lshl_add_u64 v[130:131], s[4:5], 0, v[116:117]
	v_add_u32_e32 v129, v119, v118
	s_waitcnt vmcnt(4)
	v_pk_add_f32 v[114:115], v[158:159], v[166:167]
	v_pk_add_f32 v[112:113], v[156:157], v[164:165]
	global_store_dwordx4 v[136:137], v[112:115], off
	s_cbranch_vccnz .LBB0_1947
	global_load_dwordx4 v[176:179], v[130:131], off
	global_load_dwordx4 v[180:183], v[130:131], off offset:64
	global_load_dwordx4 v[184:187], v[130:131], off offset:128
	global_load_dwordx4 v[188:191], v[130:131], off offset:192
	s_waitcnt vmcnt(3)
	v_pk_mul_f32 v[118:119], v[114:115], v[178:179]
	v_pk_mul_f32 v[116:117], v[112:113], v[176:177]
	s_nop 0
	v_cvt_pk_bf16_f32 v116, v116, v117
	v_cvt_pk_bf16_f32 v117, v118, v119
	ds_write_b64 v129, v[116:117]
.LBB0_1947:
	s_and_b64 vcc, exec, s[0:1]
	v_pk_add_f32 v[118:119], v[154:155], v[170:171]
	v_pk_add_f32 v[116:117], v[152:153], v[168:169]
	global_store_dwordx4 v[136:137], v[116:119], off offset:64
	s_cbranch_vccnz .LBB0_1949
	s_waitcnt vmcnt(3)
	v_pk_mul_f32 v[122:123], v[118:119], v[182:183]
	v_pk_mul_f32 v[120:121], v[116:117], v[180:181]
	s_nop 0
	v_cvt_pk_bf16_f32 v120, v120, v121
	v_cvt_pk_bf16_f32 v121, v122, v123
	ds_write_b64 v129, v[120:121] offset:32
.LBB0_1949:
	s_and_b64 vcc, exec, s[0:1]
	v_pk_add_f32 v[122:123], v[150:151], v[174:175]
	v_pk_add_f32 v[120:121], v[148:149], v[172:173]
	global_store_dwordx4 v[136:137], v[120:123], off offset:128
	s_cbranch_vccnz .LBB0_1951
	s_waitcnt vmcnt(3)
	v_pk_mul_f32 v[126:127], v[122:123], v[186:187]
	v_pk_mul_f32 v[124:125], v[120:121], v[184:185]
	s_nop 0
	v_cvt_pk_bf16_f32 v124, v124, v125
	v_cvt_pk_bf16_f32 v125, v126, v127
	ds_write_b64 v129, v[124:125] offset:64
.LBB0_1951:
	s_and_b64 vcc, exec, s[0:1]
	v_pk_add_f32 v[126:127], v[146:147], v[194:195]
	v_pk_add_f32 v[124:125], v[144:145], v[192:193]
	global_store_dwordx4 v[136:137], v[124:127], off offset:192
	s_cbranch_vccnz .LBB0_1953
	s_waitcnt vmcnt(3)
	v_pk_mul_f32 v[136:137], v[126:127], v[190:191]
	v_pk_mul_f32 v[142:143], v[124:125], v[188:189]
	s_nop 0
	v_cvt_pk_bf16_f32 v142, v142, v143
	v_cvt_pk_bf16_f32 v143, v136, v137
	ds_write_b64 v129, v[142:143] offset:96

; DI unsigned pk2(float lo, float hi) { f32x2 v = {lo, hi}; return __builtin_bit_cast(unsigned, __builtin_convertvector(v, bfx2)); }
; DI void resid_tile(const Params& p, const bf16_t* A, int K, const bf16_t* W, const float* xold, const float* gnext, int tm, int tn, bf16_t* smem) {
;     ...
; #pragma unroll
;   for (int i = 0; i < 8; ++i) {
;     const int t = tm * 256 + wm * 128 + i * 16 + l15, c0 = tn * 256 + wn * 64 + quad * 4; float s = 0.f;
; #pragma unroll
;     for (int j = 0; j < 4; ++j) {
;       const size_t off = (size_t)t * D_ + c0 + j * 16;
;       const f32x4 xn = *(const f32x4*)(xold + off) + acc[i][j];
;       *(f32x4*)(p.out + off) = xn;
;       s += xn[0] * xn[0] + xn[1] * xn[1] + xn[2] * xn[2] + xn[3] * xn[3];
;       if (gnext) { const f32x4 gv = *(const f32x4*)(gnext + c0 + j * 16); *(u32x2*)(stg + (i * 16 + l15) * STG_LD + j * 16 + quad * 4) = (u32x2){pk2(xn[0] * gv[0], xn[1] * gv[1]), pk2(xn[2] * gv[2], xn[3] * gv[3])}; }
;     }
;     s += __shfl_xor(s, 16); s += __shfl_xor(s, 32);
;     if (quad == 0) ((float*)(p.ws + O_SSQ))[(size_t)t * 16 + tn * 4 + wn] = s;
.LBB0_1955:
	s_or_b64 exec, exec, s[16:17]
	v_or_b32_e32 v112, 16, v134
	s_waitcnt lgkmcnt(0)
	v_ashrrev_i32_e32 v113, 31, v112
	v_readlane_b32 s28, v241, 2
	v_lshlrev_b64 v[114:115], 12, v[112:113]
	v_readlane_b32 s30, v241, 4
	v_readlane_b32 s31, v241, 5
	s_and_b64 vcc, exec, s[0:1]
	v_readlane_b32 s29, v241, 3
	v_lshl_add_u64 v[114:115], s[30:31], 0, v[114:115]
	v_lshl_add_u64 v[114:115], v[132:133], 2, v[114:115]
	v_lshl_add_u64 v[212:213], v[212:213], 0, s[98:99]
	global_load_dwordx4 v[164:167], v[212:213], off
	global_load_dwordx4 v[168:171], v[212:213], off offset:64
	global_load_dwordx4 v[172:175], v[212:213], off offset:128
	global_load_dwordx4 v[192:195], v[212:213], off offset:192
	s_waitcnt vmcnt(8)
	v_pk_add_f32 v[110:111], v[110:111], v[198:199]
	v_pk_add_f32 v[108:109], v[108:109], v[196:197]
	global_store_dwordx4 v[114:115], v[108:111], off
	s_cbranch_vccnz .LBB0_1957
	v_pk_mul_f32 v[122:123], v[110:111], v[178:179]
	v_pk_mul_f32 v[120:121], v[108:109], v[176:177]
	s_nop 0
	v_cvt_pk_bf16_f32 v120, v120, v121
	v_cvt_pk_bf16_f32 v121, v122, v123
	ds_write_b64 v129, v[120:121] offset:2304
.LBB0_1957:
	s_and_b64 vcc, exec, s[0:1]
	v_pk_add_f32 v[106:107], v[106:107], v[202:203]
	v_pk_add_f32 v[104:105], v[104:105], v[200:201]
	global_store_dwordx4 v[114:115], v[104:107], off offset:64
	s_cbranch_vccnz .LBB0_1959
	v_pk_mul_f32 v[122:123], v[106:107], v[182:183]
	v_pk_mul_f32 v[120:121], v[104:105], v[180:181]
	s_nop 0
	v_cvt_pk_bf16_f32 v120, v120, v121
	v_cvt_pk_bf16_f32 v121, v122, v123
	ds_write_b64 v129, v[120:121] offset:2336
.LBB0_1959:
	s_and_b64 vcc, exec, s[0:1]
	v_pk_add_f32 v[102:103], v[102:103], v[206:207]
	v_pk_add_f32 v[100:101], v[100:101], v[204:205]
	global_store_dwordx4 v[114:115], v[100:103], off offset:128
	s_cbranch_vccnz .LBB0_1961
	v_pk_mul_f32 v[122:123], v[102:103], v[186:187]
	v_pk_mul_f32 v[120:121], v[100:101], v[184:185]
	s_nop 0
	v_cvt_pk_bf16_f32 v120, v120, v121
	v_cvt_pk_bf16_f32 v121, v122, v123
	ds_write_b64 v129, v[120:121] offset:2368
.LBB0_1961:
	s_and_b64 vcc, exec, s[0:1]
	v_pk_add_f32 v[98:99], v[98:99], v[210:211]
	v_pk_add_f32 v[96:97], v[96:97], v[208:209]
	global_store_dwordx4 v[114:115], v[96:99], off offset:192
	s_cbranch_vccnz .LBB0_1963
	v_pk_mul_f32 v[114:115], v[98:99], v[190:191]
	v_pk_mul_f32 v[120:121], v[96:97], v[188:189]
	s_nop 0
	v_cvt_pk_bf16_f32 v120, v120, v121
	v_cvt_pk_bf16_f32 v121, v114, v115
	ds_write_b64 v129, v[120:121] offset:2400

; DI unsigned pk2(float lo, float hi) { f32x2 v = {lo, hi}; return __builtin_bit_cast(unsigned, __builtin_convertvector(v, bfx2)); }
; DI void resid_tile(const Params& p, const bf16_t* A, int K, const bf16_t* W, const float* xold, const float* gnext, int tm, int tn, bf16_t* smem) {
;     ...
; #pragma unroll
;   for (int i = 0; i < 8; ++i) {
;     const int t = tm * 256 + wm * 128 + i * 16 + l15, c0 = tn * 256 + wn * 64 + quad * 4; float s = 0.f;
; #pragma unroll
;     for (int j = 0; j < 4; ++j) {
;       const size_t off = (size_t)t * D_ + c0 + j * 16;
;       const f32x4 xn = *(const f32x4*)(xold + off) + acc[i][j];
;       *(f32x4*)(p.out + off) = xn;
;       s += xn[0] * xn[0] + xn[1] * xn[1] + xn[2] * xn[2] + xn[3] * xn[3];
;       if (gnext) { const f32x4 gv = *(const f32x4*)(gnext + c0 + j * 16); *(u32x2*)(stg + (i * 16 + l15) * STG_LD + j * 16 + quad * 4) = (u32x2){pk2(xn[0] * gv[0], xn[1] * gv[1]), pk2(xn[2] * gv[2], xn[3] * gv[3])}; }
;     }
;     s += __shfl_xor(s, 16); s += __shfl_xor(s, 32);
;     if (quad == 0) ((float*)(p.ws + O_SSQ))[(size_t)t * 16 + tn * 4 + wn] = s;
.LBB0_1965:
	s_or_b64 exec, exec, s[16:17]
	v_or_b32_e32 v96, 32, v134
	s_waitcnt lgkmcnt(0)
	v_ashrrev_i32_e32 v97, 31, v96
	v_readlane_b32 s28, v241, 2
	v_lshlrev_b64 v[98:99], 12, v[96:97]
	v_readlane_b32 s30, v241, 4
	v_readlane_b32 s31, v241, 5
	s_and_b64 vcc, exec, s[0:1]
	v_readlane_b32 s29, v241, 3
	v_lshl_add_u64 v[98:99], s[30:31], 0, v[98:99]
	v_lshl_add_u64 v[98:99], v[132:133], 2, v[98:99]
	v_lshl_add_u64 v[212:213], v[212:213], 0, s[98:99]
	global_load_dwordx4 v[196:199], v[212:213], off
	global_load_dwordx4 v[200:203], v[212:213], off offset:64
	global_load_dwordx4 v[204:207], v[212:213], off offset:128
	global_load_dwordx4 v[208:211], v[212:213], off offset:192
	s_waitcnt vmcnt(8)
	v_pk_add_f32 v[94:95], v[94:95], v[166:167]
	v_pk_add_f32 v[92:93], v[92:93], v[164:165]
	global_store_dwordx4 v[98:99], v[92:95], off
	s_cbranch_vccnz .LBB0_1967
	v_pk_mul_f32 v[102:103], v[94:95], v[178:179]
	v_pk_mul_f32 v[100:101], v[92:93], v[176:177]
	s_nop 0
	v_cvt_pk_bf16_f32 v100, v100, v101
	v_cvt_pk_bf16_f32 v101, v102, v103
	ds_write_b64 v129, v[100:101] offset:4608
.LBB0_1967:
	s_and_b64 vcc, exec, s[0:1]
	v_pk_add_f32 v[90:91], v[90:91], v[170:171]
	v_pk_add_f32 v[88:89], v[88:89], v[168:169]
	global_store_dwordx4 v[98:99], v[88:91], off offset:64
	s_cbranch_vccnz .LBB0_1969
	v_pk_mul_f32 v[102:103], v[90:91], v[182:183]
	v_pk_mul_f32 v[100:101], v[88:89], v[180:181]
	s_nop 0
	v_cvt_pk_bf16_f32 v100, v100, v101
	v_cvt_pk_bf16_f32 v101, v102, v103
	ds_write_b64 v129, v[100:101] offset:4640
.LBB0_1969:
	s_and_b64 vcc, exec, s[0:1]
	v_pk_add_f32 v[86:87], v[86:87], v[174:175]
	v_pk_add_f32 v[84:85], v[84:85], v[172:173]
	global_store_dwordx4 v[98:99], v[84:87], off offset:128
	s_cbranch_vccnz .LBB0_1971
	v_pk_mul_f32 v[102:103], v[86:87], v[186:187]
	v_pk_mul_f32 v[100:101], v[84:85], v[184:185]
	s_nop 0
	v_cvt_pk_bf16_f32 v100, v100, v101
	v_cvt_pk_bf16_f32 v101, v102, v103
	ds_write_b64 v129, v[100:101] offset:4672
.LBB0_1971:
	s_and_b64 vcc, exec, s[0:1]
	v_pk_add_f32 v[82:83], v[82:83], v[194:195]
	v_pk_add_f32 v[80:81], v[80:81], v[192:193]
	global_store_dwordx4 v[98:99], v[80:83], off offset:192
	s_cbranch_vccnz .LBB0_1973
	v_pk_mul_f32 v[100:101], v[82:83], v[190:191]
	v_pk_mul_f32 v[98:99], v[80:81], v[188:189]
	s_nop 0
	v_cvt_pk_bf16_f32 v98, v98, v99
	v_cvt_pk_bf16_f32 v99, v100, v101
	ds_write_b64 v129, v[98:99] offset:4704

; DI unsigned pk2(float lo, float hi) { f32x2 v = {lo, hi}; return __builtin_bit_cast(unsigned, __builtin_convertvector(v, bfx2)); }
; DI void resid_tile(const Params& p, const bf16_t* A, int K, const bf16_t* W, const float* xold, const float* gnext, int tm, int tn, bf16_t* smem) {
;     ...
; #pragma unroll
;   for (int i = 0; i < 8; ++i) {
;     const int t = tm * 256 + wm * 128 + i * 16 + l15, c0 = tn * 256 + wn * 64 + quad * 4; float s = 0.f;
; #pragma unroll
;     for (int j = 0; j < 4; ++j) {
;       const size_t off = (size_t)t * D_ + c0 + j * 16;
;       const f32x4 xn = *(const f32x4*)(xold + off) + acc[i][j];
;       *(f32x4*)(p.out + off) = xn;
;       s += xn[0] * xn[0] + xn[1] * xn[1] + xn[2] * xn[2] + xn[3] * xn[3];
;       if (gnext) { const f32x4 gv = *(const f32x4*)(gnext + c0 + j * 16); *(u32x2*)(stg + (i * 16 + l15) * STG_LD + j * 16 + quad * 4) = (u32x2){pk2(xn[0] * gv[0], xn[1] * gv[1]), pk2(xn[2] * gv[2], xn[3] * gv[3])}; }
;     }
;     s += __shfl_xor(s, 16); s += __shfl_xor(s, 32);
;     if (quad == 0) ((float*)(p.ws + O_SSQ))[(size_t)t * 16 + tn * 4 + wn] = s;
.LBB0_1975:
	s_or_b64 exec, exec, s[16:17]
	v_or_b32_e32 v80, 48, v134
	s_waitcnt lgkmcnt(0)
	v_ashrrev_i32_e32 v81, 31, v80
	v_readlane_b32 s28, v241, 2
	v_lshlrev_b64 v[82:83], 12, v[80:81]
	v_readlane_b32 s30, v241, 4
	v_readlane_b32 s31, v241, 5
	s_and_b64 vcc, exec, s[0:1]
	v_readlane_b32 s29, v241, 3
	v_lshl_add_u64 v[82:83], s[30:31], 0, v[82:83]
	v_lshl_add_u64 v[82:83], v[132:133], 2, v[82:83]
	v_lshl_add_u64 v[212:213], v[212:213], 0, s[98:99]
	global_load_dwordx4 v[164:167], v[212:213], off
	global_load_dwordx4 v[168:171], v[212:213], off offset:64
	global_load_dwordx4 v[172:175], v[212:213], off offset:128
	global_load_dwordx4 v[192:195], v[212:213], off offset:192
	s_waitcnt vmcnt(8)
	v_pk_add_f32 v[78:79], v[78:79], v[198:199]
	v_pk_add_f32 v[76:77], v[76:77], v[196:197]
	global_store_dwordx4 v[82:83], v[76:79], off
	s_cbranch_vccnz .LBB0_1977
	v_pk_mul_f32 v[86:87], v[78:79], v[178:179]
	v_pk_mul_f32 v[84:85], v[76:77], v[176:177]
	s_nop 0
	v_cvt_pk_bf16_f32 v84, v84, v85
	v_cvt_pk_bf16_f32 v85, v86, v87
	ds_write_b64 v129, v[84:85] offset:6912
.LBB0_1977:
	s_and_b64 vcc, exec, s[0:1]
	v_pk_add_f32 v[74:75], v[74:75], v[202:203]
	v_pk_add_f32 v[72:73], v[72:73], v[200:201]
	global_store_dwordx4 v[82:83], v[72:75], off offset:64
	s_cbranch_vccnz .LBB0_1979
	v_pk_mul_f32 v[86:87], v[74:75], v[182:183]
	v_pk_mul_f32 v[84:85], v[72:73], v[180:181]
	s_nop 0
	v_cvt_pk_bf16_f32 v84, v84, v85
	v_cvt_pk_bf16_f32 v85, v86, v87
	ds_write_b64 v129, v[84:85] offset:6944
.LBB0_1979:
	s_and_b64 vcc, exec, s[0:1]
	v_pk_add_f32 v[70:71], v[70:71], v[206:207]
	v_pk_add_f32 v[68:69], v[68:69], v[204:205]
	global_store_dwordx4 v[82:83], v[68:71], off offset:128
	s_cbranch_vccnz .LBB0_1981
	v_pk_mul_f32 v[86:87], v[70:71], v[186:187]
	v_pk_mul_f32 v[84:85], v[68:69], v[184:185]
	s_nop 0
	v_cvt_pk_bf16_f32 v84, v84, v85
	v_cvt_pk_bf16_f32 v85, v86, v87
	ds_write_b64 v129, v[84:85] offset:6976
.LBB0_1981:
	s_and_b64 vcc, exec, s[0:1]
	v_pk_add_f32 v[66:67], v[66:67], v[210:211]
	v_pk_add_f32 v[64:65], v[64:65], v[208:209]
	global_store_dwordx4 v[82:83], v[64:67], off offset:192
	s_cbranch_vccnz .LBB0_1983
	v_pk_mul_f32 v[84:85], v[66:67], v[190:191]
	v_pk_mul_f32 v[82:83], v[64:65], v[188:189]
	s_nop 0
	v_cvt_pk_bf16_f32 v82, v82, v83
	v_cvt_pk_bf16_f32 v83, v84, v85
	ds_write_b64 v129, v[82:83] offset:7008

; DI unsigned pk2(float lo, float hi) { f32x2 v = {lo, hi}; return __builtin_bit_cast(unsigned, __builtin_convertvector(v, bfx2)); }
; DI void resid_tile(const Params& p, const bf16_t* A, int K, const bf16_t* W, const float* xold, const float* gnext, int tm, int tn, bf16_t* smem) {
;     ...
; #pragma unroll
;   for (int i = 0; i < 8; ++i) {
;     const int t = tm * 256 + wm * 128 + i * 16 + l15, c0 = tn * 256 + wn * 64 + quad * 4; float s = 0.f;
; #pragma unroll
;     for (int j = 0; j < 4; ++j) {
;       const size_t off = (size_t)t * D_ + c0 + j * 16;
;       const f32x4 xn = *(const f32x4*)(xold + off) + acc[i][j];
;       *(f32x4*)(p.out + off) = xn;
;       s += xn[0] * xn[0] + xn[1] * xn[1] + xn[2] * xn[2] + xn[3] * xn[3];
;       if (gnext) { const f32x4 gv = *(const f32x4*)(gnext + c0 + j * 16); *(u32x2*)(stg + (i * 16 + l15) * STG_LD + j * 16 + quad * 4) = (u32x2){pk2(xn[0] * gv[0], xn[1] * gv[1]), pk2(xn[2] * gv[2], xn[3] * gv[3])}; }
;     }
;     s += __shfl_xor(s, 16); s += __shfl_xor(s, 32);
;     if (quad == 0) ((float*)(p.ws + O_SSQ))[(size_t)t * 16 + tn * 4 + wn] = s;
.LBB0_1985:
	s_or_b64 exec, exec, s[16:17]
	v_or_b32_e32 v64, 64, v134
	s_waitcnt lgkmcnt(0)
	v_ashrrev_i32_e32 v65, 31, v64
	v_readlane_b32 s28, v241, 2
	v_lshlrev_b64 v[66:67], 12, v[64:65]
	v_readlane_b32 s30, v241, 4
	v_readlane_b32 s31, v241, 5
	s_and_b64 vcc, exec, s[0:1]
	v_readlane_b32 s29, v241, 3
	v_lshl_add_u64 v[66:67], s[30:31], 0, v[66:67]
	v_lshl_add_u64 v[66:67], v[132:133], 2, v[66:67]
	v_lshl_add_u64 v[212:213], v[212:213], 0, s[98:99]
	global_load_dwordx4 v[196:199], v[212:213], off
	global_load_dwordx4 v[200:203], v[212:213], off offset:64
	global_load_dwordx4 v[204:207], v[212:213], off offset:128
	global_load_dwordx4 v[208:211], v[212:213], off offset:192
	s_waitcnt vmcnt(8)
	v_pk_add_f32 v[62:63], v[62:63], v[166:167]
	v_pk_add_f32 v[60:61], v[60:61], v[164:165]
	global_store_dwordx4 v[66:67], v[60:63], off
	s_cbranch_vccnz .LBB0_1987
	v_pk_mul_f32 v[70:71], v[62:63], v[178:179]
	v_pk_mul_f32 v[68:69], v[60:61], v[176:177]
	s_nop 0
	v_cvt_pk_bf16_f32 v68, v68, v69
	v_cvt_pk_bf16_f32 v69, v70, v71
	ds_write_b64 v129, v[68:69] offset:9216
.LBB0_1987:
	s_and_b64 vcc, exec, s[0:1]
	v_pk_add_f32 v[58:59], v[58:59], v[170:171]
	v_pk_add_f32 v[56:57], v[56:57], v[168:169]
	global_store_dwordx4 v[66:67], v[56:59], off offset:64
	s_cbranch_vccnz .LBB0_1989
	v_pk_mul_f32 v[70:71], v[58:59], v[182:183]
	v_pk_mul_f32 v[68:69], v[56:57], v[180:181]
	s_nop 0
	v_cvt_pk_bf16_f32 v68, v68, v69
	v_cvt_pk_bf16_f32 v69, v70, v71
	ds_write_b64 v129, v[68:69] offset:9248
.LBB0_1989:
	s_and_b64 vcc, exec, s[0:1]
	v_pk_add_f32 v[54:55], v[54:55], v[174:175]
	v_pk_add_f32 v[52:53], v[52:53], v[172:173]
	global_store_dwordx4 v[66:67], v[52:55], off offset:128
	s_cbranch_vccnz .LBB0_1991
	v_pk_mul_f32 v[70:71], v[54:55], v[186:187]
	v_pk_mul_f32 v[68:69], v[52:53], v[184:185]
	s_nop 0
	v_cvt_pk_bf16_f32 v68, v68, v69
	v_cvt_pk_bf16_f32 v69, v70, v71
	ds_write_b64 v129, v[68:69] offset:9280
.LBB0_1991:
	s_and_b64 vcc, exec, s[0:1]
	v_pk_add_f32 v[50:51], v[50:51], v[194:195]
	v_pk_add_f32 v[48:49], v[48:49], v[192:193]
	global_store_dwordx4 v[66:67], v[48:51], off offset:192
	s_cbranch_vccnz .LBB0_1993
	v_pk_mul_f32 v[68:69], v[50:51], v[190:191]
	v_pk_mul_f32 v[66:67], v[48:49], v[188:189]
	s_nop 0
	v_cvt_pk_bf16_f32 v66, v66, v67
	v_cvt_pk_bf16_f32 v67, v68, v69
	ds_write_b64 v129, v[66:67] offset:9312

; DI unsigned pk2(float lo, float hi) { f32x2 v = {lo, hi}; return __builtin_bit_cast(unsigned, __builtin_convertvector(v, bfx2)); }
; DI void resid_tile(const Params& p, const bf16_t* A, int K, const bf16_t* W, const float* xold, const float* gnext, int tm, int tn, bf16_t* smem) {
;     ...
;   for (int i = 0; i < 8; ++i) {
;     const int t = tm * 256 + wm * 128 + i * 16 + l15, c0 = tn * 256 + wn * 64 + quad * 4; float s = 0.f;
; #pragma unroll
;     for (int j = 0; j < 4; ++j) {
;       const size_t off = (size_t)t * D_ + c0 + j * 16;
;       const f32x4 xn = *(const f32x4*)(xold + off) + acc[i][j];
;       *(f32x4*)(p.out + off) = xn;
;       s += xn[0] * xn[0] + xn[1] * xn[1] + xn[2] * xn[2] + xn[3] * xn[3];
;       if (gnext) { const f32x4 gv = *(const f32x4*)(gnext + c0 + j * 16); *(u32x2*)(stg + (i * 16 + l15) * STG_LD + j * 16 + quad * 4) = (u32x2){pk2(xn[0] * gv[0], xn[1] * gv[1]), pk2(xn[2] * gv[2], xn[3] * gv[3])}; }
;     }
.LBB0_1995:
	s_or_b64 exec, exec, s[16:17]
	v_or_b32_e32 v48, 0x50, v134
	s_waitcnt lgkmcnt(0)
	v_ashrrev_i32_e32 v49, 31, v48
	v_readlane_b32 s28, v241, 2
	v_lshlrev_b64 v[50:51], 12, v[48:49]
	v_readlane_b32 s30, v241, 4
	v_readlane_b32 s31, v241, 5
	s_and_b64 vcc, exec, s[0:1]
	v_readlane_b32 s29, v241, 3
	v_lshl_add_u64 v[50:51], s[30:31], 0, v[50:51]
	v_lshl_add_u64 v[50:51], v[132:133], 2, v[50:51]
	v_lshl_add_u64 v[212:213], v[212:213], 0, s[98:99]
	global_load_dwordx4 v[164:167], v[212:213], off
	global_load_dwordx4 v[168:171], v[212:213], off offset:64
	global_load_dwordx4 v[172:175], v[212:213], off offset:128
	global_load_dwordx4 v[192:195], v[212:213], off offset:192
	s_waitcnt vmcnt(8)
	v_pk_add_f32 v[46:47], v[46:47], v[198:199]
	v_pk_add_f32 v[44:45], v[44:45], v[196:197]
	global_store_dwordx4 v[50:51], v[44:47], off
	s_cbranch_vccnz .LBB0_1997
	v_pk_mul_f32 v[54:55], v[46:47], v[178:179]
	v_pk_mul_f32 v[52:53], v[44:45], v[176:177]
	s_nop 0
	v_cvt_pk_bf16_f32 v52, v52, v53
	v_cvt_pk_bf16_f32 v53, v54, v55
	ds_write_b64 v129, v[52:53] offset:11520
.LBB0_1997:
	s_and_b64 vcc, exec, s[0:1]
	v_pk_add_f32 v[42:43], v[42:43], v[202:203]
	v_pk_add_f32 v[40:41], v[40:41], v[200:201]
	global_store_dwordx4 v[50:51], v[40:43], off offset:64
	s_cbranch_vccnz .LBB0_1999
	v_pk_mul_f32 v[54:55], v[42:43], v[182:183]
	v_pk_mul_f32 v[52:53], v[40:41], v[180:181]
	s_nop 0
	v_cvt_pk_bf16_f32 v52, v52, v53
	v_cvt_pk_bf16_f32 v53, v54, v55
	ds_write_b64 v129, v[52:53] offset:11552
.LBB0_1999:
	s_and_b64 vcc, exec, s[0:1]
	v_pk_add_f32 v[38:39], v[38:39], v[206:207]
	v_pk_add_f32 v[36:37], v[36:37], v[204:205]
	global_store_dwordx4 v[50:51], v[36:39], off offset:128
	s_cbranch_vccnz .LBB0_2001
	v_pk_mul_f32 v[54:55], v[38:39], v[186:187]
	v_pk_mul_f32 v[52:53], v[36:37], v[184:185]
	s_nop 0
	v_cvt_pk_bf16_f32 v52, v52, v53
	v_cvt_pk_bf16_f32 v53, v54, v55
	ds_write_b64 v129, v[52:53] offset:11584
.LBB0_2001:
	s_and_b64 vcc, exec, s[0:1]
	v_pk_add_f32 v[34:35], v[34:35], v[210:211]
	v_pk_add_f32 v[32:33], v[32:33], v[208:209]
	global_store_dwordx4 v[50:51], v[32:35], off offset:192
	s_cbranch_vccnz .LBB0_2003
	v_pk_mul_f32 v[52:53], v[34:35], v[190:191]
	v_pk_mul_f32 v[50:51], v[32:33], v[188:189]
	s_nop 0
	v_cvt_pk_bf16_f32 v50, v50, v51
	v_cvt_pk_bf16_f32 v51, v52, v53
	ds_write_b64 v129, v[50:51] offset:11616

; DI unsigned pk2(float lo, float hi) { f32x2 v = {lo, hi}; return __builtin_bit_cast(unsigned, __builtin_convertvector(v, bfx2)); }
; DI void resid_tile(const Params& p, const bf16_t* A, int K, const bf16_t* W, const float* xold, const float* gnext, int tm, int tn, bf16_t* smem) {
;     ...
;   for (int i = 0; i < 8; ++i) {
;     const int t = tm * 256 + wm * 128 + i * 16 + l15, c0 = tn * 256 + wn * 64 + quad * 4; float s = 0.f;
; #pragma unroll
;     for (int j = 0; j < 4; ++j) {
;       const size_t off = (size_t)t * D_ + c0 + j * 16;
;       const f32x4 xn = *(const f32x4*)(xold + off) + acc[i][j];
;       *(f32x4*)(p.out + off) = xn;
;       s += xn[0] * xn[0] + xn[1] * xn[1] + xn[2] * xn[2] + xn[3] * xn[3];
;       if (gnext) { const f32x4 gv = *(const f32x4*)(gnext + c0 + j * 16); *(u32x2*)(stg + (i * 16 + l15) * STG_LD + j * 16 + quad * 4) = (u32x2){pk2(xn[0] * gv[0], xn[1] * gv[1]), pk2(xn[2] * gv[2], xn[3] * gv[3])}; }
;     }
.LBB0_2005:
	s_or_b64 exec, exec, s[16:17]
	v_or_b32_e32 v32, 0x60, v134
	s_waitcnt lgkmcnt(0)
	v_ashrrev_i32_e32 v33, 31, v32
	v_readlane_b32 s28, v241, 2
	v_lshlrev_b64 v[34:35], 12, v[32:33]
	v_readlane_b32 s30, v241, 4
	v_readlane_b32 s31, v241, 5
	s_and_b64 vcc, exec, s[0:1]
	v_readlane_b32 s29, v241, 3
	v_lshl_add_u64 v[34:35], s[30:31], 0, v[34:35]
	v_lshl_add_u64 v[34:35], v[132:133], 2, v[34:35]
	v_lshl_add_u64 v[212:213], v[212:213], 0, s[98:99]
	global_load_dwordx4 v[196:199], v[212:213], off
	global_load_dwordx4 v[200:203], v[212:213], off offset:64
	global_load_dwordx4 v[204:207], v[212:213], off offset:128
	global_load_dwordx4 v[208:211], v[212:213], off offset:192
	s_waitcnt vmcnt(8)
	v_pk_add_f32 v[30:31], v[30:31], v[166:167]
	v_pk_add_f32 v[28:29], v[28:29], v[164:165]
	global_store_dwordx4 v[34:35], v[28:31], off
	s_cbranch_vccnz .LBB0_2007
	v_pk_mul_f32 v[38:39], v[30:31], v[178:179]
	v_pk_mul_f32 v[36:37], v[28:29], v[176:177]
	s_nop 0
	v_cvt_pk_bf16_f32 v36, v36, v37
	v_cvt_pk_bf16_f32 v37, v38, v39
	ds_write_b64 v129, v[36:37] offset:13824
.LBB0_2007:
	s_and_b64 vcc, exec, s[0:1]
	v_pk_add_f32 v[26:27], v[26:27], v[170:171]
	v_pk_add_f32 v[24:25], v[24:25], v[168:169]
	global_store_dwordx4 v[34:35], v[24:27], off offset:64
	s_cbranch_vccnz .LBB0_2009
	v_pk_mul_f32 v[38:39], v[26:27], v[182:183]
	v_pk_mul_f32 v[36:37], v[24:25], v[180:181]
	s_nop 0
	v_cvt_pk_bf16_f32 v36, v36, v37
	v_cvt_pk_bf16_f32 v37, v38, v39
	ds_write_b64 v129, v[36:37] offset:13856
.LBB0_2009:
	s_and_b64 vcc, exec, s[0:1]
	v_pk_add_f32 v[22:23], v[22:23], v[174:175]
	v_pk_add_f32 v[20:21], v[20:21], v[172:173]
	global_store_dwordx4 v[34:35], v[20:23], off offset:128
	s_cbranch_vccnz .LBB0_2011
	v_pk_mul_f32 v[38:39], v[22:23], v[186:187]
	v_pk_mul_f32 v[36:37], v[20:21], v[184:185]
	s_nop 0
	v_cvt_pk_bf16_f32 v36, v36, v37
	v_cvt_pk_bf16_f32 v37, v38, v39
	ds_write_b64 v129, v[36:37] offset:13888
.LBB0_2011:
	s_and_b64 vcc, exec, s[0:1]
	v_pk_add_f32 v[18:19], v[18:19], v[194:195]
	v_pk_add_f32 v[16:17], v[16:17], v[192:193]
	global_store_dwordx4 v[34:35], v[16:19], off offset:192
	s_cbranch_vccnz .LBB0_2013
	v_pk_mul_f32 v[36:37], v[18:19], v[190:191]
	v_pk_mul_f32 v[34:35], v[16:17], v[188:189]
	s_nop 0
	v_cvt_pk_bf16_f32 v34, v34, v35
	v_cvt_pk_bf16_f32 v35, v36, v37
	ds_write_b64 v129, v[34:35] offset:13920

; DI unsigned pk2(float lo, float hi) { f32x2 v = {lo, hi}; return __builtin_bit_cast(unsigned, __builtin_convertvector(v, bfx2)); }
; DI void resid_tile(const Params& p, const bf16_t* A, int K, const bf16_t* W, const float* xold, const float* gnext, int tm, int tn, bf16_t* smem) {
;     ...
;   for (int i = 0; i < 8; ++i) {
;     const int t = tm * 256 + wm * 128 + i * 16 + l15, c0 = tn * 256 + wn * 64 + quad * 4; float s = 0.f;
; #pragma unroll
;     for (int j = 0; j < 4; ++j) {
;       const size_t off = (size_t)t * D_ + c0 + j * 16;
;       const f32x4 xn = *(const f32x4*)(xold + off) + acc[i][j];
;       *(f32x4*)(p.out + off) = xn;
;       s += xn[0] * xn[0] + xn[1] * xn[1] + xn[2] * xn[2] + xn[3] * xn[3];
;       if (gnext) { const f32x4 gv = *(const f32x4*)(gnext + c0 + j * 16); *(u32x2*)(stg + (i * 16 + l15) * STG_LD + j * 16 + quad * 4) = (u32x2){pk2(xn[0] * gv[0], xn[1] * gv[1]), pk2(xn[2] * gv[2], xn[3] * gv[3])}; }
;     }
.LBB0_2015:
	s_or_b64 exec, exec, s[16:17]
	v_or_b32_e32 v16, 0x70, v134
	s_waitcnt lgkmcnt(0)
	v_ashrrev_i32_e32 v17, 31, v16
	v_readlane_b32 s28, v241, 2
	v_lshlrev_b64 v[18:19], 12, v[16:17]
	v_readlane_b32 s30, v241, 4
	v_readlane_b32 s31, v241, 5
	s_and_b64 vcc, exec, s[0:1]
	v_readlane_b32 s29, v241, 3
	v_lshl_add_u64 v[18:19], s[30:31], 0, v[18:19]
	v_lshl_add_u64 v[18:19], v[132:133], 2, v[18:19]
	s_waitcnt vmcnt(4)
	v_pk_add_f32 v[10:11], v[10:11], v[198:199]
	v_pk_add_f32 v[8:9], v[8:9], v[196:197]
	global_store_dwordx4 v[18:19], v[8:11], off
	s_cbranch_vccnz .LBB0_2017
	v_pk_mul_f32 v[22:23], v[10:11], v[178:179]
	v_pk_mul_f32 v[20:21], v[8:9], v[176:177]
	s_nop 0
	v_cvt_pk_bf16_f32 v20, v20, v21
	v_cvt_pk_bf16_f32 v21, v22, v23
	ds_write_b64 v129, v[20:21] offset:16128
.LBB0_2017:
	s_and_b64 vcc, exec, s[0:1]
	v_pk_add_f32 v[6:7], v[6:7], v[202:203]
	v_pk_add_f32 v[4:5], v[4:5], v[200:201]
	global_store_dwordx4 v[18:19], v[4:7], off offset:64
	s_cbranch_vccnz .LBB0_2019
	v_pk_mul_f32 v[22:23], v[6:7], v[182:183]
	v_pk_mul_f32 v[20:21], v[4:5], v[180:181]
	s_nop 0
	v_cvt_pk_bf16_f32 v20, v20, v21
	v_cvt_pk_bf16_f32 v21, v22, v23
	ds_write_b64 v129, v[20:21] offset:16160
.LBB0_2019:
	s_and_b64 vcc, exec, s[0:1]
	v_pk_add_f32 v[2:3], v[2:3], v[206:207]
	v_pk_add_f32 v[0:1], v[0:1], v[204:205]
	global_store_dwordx4 v[18:19], v[0:3], off offset:128
	s_cbranch_vccnz .LBB0_2021
	v_pk_mul_f32 v[22:23], v[2:3], v[186:187]
	v_pk_mul_f32 v[20:21], v[0:1], v[184:185]
	s_nop 0
	v_cvt_pk_bf16_f32 v20, v20, v21
	v_cvt_pk_bf16_f32 v21, v22, v23
	ds_write_b64 v129, v[20:21] offset:16192
.LBB0_2021:
	s_and_b64 vcc, exec, s[0:1]
	v_pk_add_f32 v[14:15], v[14:15], v[210:211]
	v_pk_add_f32 v[12:13], v[12:13], v[208:209]
	global_store_dwordx4 v[18:19], v[12:15], off offset:192
	s_cbranch_vccnz .LBB0_2023
	v_pk_mul_f32 v[20:21], v[14:15], v[190:191]
	v_pk_mul_f32 v[18:19], v[12:13], v[188:189]
	s_nop 0
	v_cvt_pk_bf16_f32 v18, v18, v19
	v_cvt_pk_bf16_f32 v19, v20, v21
	ds_write_b64 v129, v[18:19] offset:16224
